# v45 + nt (streaming) policy on the prompt-attention Q fragment loads
# baseline (speedup 1.0000x reference)
; __device__ __forceinline__ void attn_mfma_phase(LAS unsigned char* lds, const bf16* QKVb, bf16* OPART, float2* ML, int tid, int wave, int lane) {
;     ...
;         const int l0 = L0 + 32 * wave;
;         const int tok_q = (l0 + i) * d + r;
;         const bf16* qp = QKVb + (size_t)tok_q * INW + C_QA + h * 64 + 8 * hh;
;         bf16x8 qf[4];
; #pragma unroll
;         for (int ks = 0; ks < 4; ++ks) qf[ks] = *(const bf16x8*)(qp + 16 * ks);
;         __syncthreads();
;         if (item + (int)gridDim.x < 1536) issue(item + gridDim.x);
.LBB0_1018:
	s_lshl_b32 s87, s84, 8
	s_add_i32 s87, s87, s2
	s_lshl_b32 s70, s1, 1
	v_or_b32_e32 v2, s87, v133
	v_lshlrev_b32_e32 v2, s70, v2
	v_readlane_b32 s70, v254, 55
	v_readlane_b32 s71, v254, 56
	v_add_u32_e32 v148, s33, v2
	s_lshl_b32 s94, s0, 6
	v_mov_b64_e32 v[2:3], s[70:71]
	v_mad_i64_i32 v[2:3], s[70:71], v148, s3, v[2:3]
	s_ashr_i32 s95, s94, 31
	v_lshl_add_u64 v[2:3], s[94:95], 1, v[2:3]
	v_lshl_add_u64 v[2:3], v[2:3], 0, v[142:143]
	global_load_dwordx4 v[114:117], v[2:3], off nt
	global_load_dwordx4 v[118:121], v[2:3], off offset:32 nt
	global_load_dwordx4 v[122:125], v[2:3], off offset:64 nt
	global_load_dwordx4 v[126:129], v[2:3], off offset:96 nt
	s_movk_i32 s33, 128
	s_add_i32 s86, s86, s33
	s_cmpk_gt_i32 s86, 0x5ff
	s_cselect_b64 s[72:73], -1, 0
	v_add_u32_e32 v2, v135, v155
	s_and_b64 vcc, exec, s[72:73]
	s_waitcnt vmcnt(5)
	ds_write_b128 v159, v[70:73]
	s_waitcnt vmcnt(4)
	ds_write_b128 v2, v[66:69] offset:55296
	ds_write_b128 v160, v[78:81]
	ds_write_b128 v161, v[74:77] offset:55296
	ds_write_b128 v159, v[86:89] offset:18432
	ds_write_b128 v168, v[82:85] offset:55296
	ds_write_b128 v169, v[94:97]
	ds_write_b128 v170, v[90:93] offset:55296
	ds_write_b128 v159, v[102:105] offset:36864
	ds_write_b128 v171, v[98:101] offset:55296
	ds_write_b128 v172, v[110:113]
	ds_write_b128 v173, v[106:109] offset:55296
	s_waitcnt lgkmcnt(0)
	s_barrier
	s_waitcnt vmcnt(0)
	s_cbranch_vccnz .LBB0_1039
	s_mul_hi_i32 s33, s86, 0x2aaaaaab
	s_lshr_b32 s70, s33, 31
	s_ashr_i32 s96, s33, 5
	s_add_i32 s96, s96, s70
	s_mul_i32 s33, s96, 0xc0
	s_sub_i32 s70, s86, s33
	s_cmp_lt_i32 s70, 64
	s_mov_b32 s84, 0
	s_cbranch_scc1 .LBB0_1025
	s_cmpk_gt_u32 s70, 0x7f
	s_mov_b64 s[92:93], -1
	s_cbranch_scc0 .LBB0_1022
	s_add_i32 s33, s70, 0xffffff80
	s_lshr_b32 s84, s33, 2
	s_and_b32 s33, s70, 3
	s_mov_b64 s[92:93], 0
